# P0: nt (non-temporal) hint on the single-use f32 source loads (weights, x rows, cache_k/v); gain loads stay cached
# speedup vs baseline: 1.0039x; 1.0029x over previous
.LBB0_11:
	s_cmpk_gt_i32 s28, 0x3fff
	s_mov_b64 s[4:5], -1
	s_cbranch_scc0 .LBB0_42
	s_cmpk_gt_u32 s28, 0x5fff
	s_cbranch_scc0 .LBB0_39
	s_cmpk_gt_u32 s28, 0xdfff
	s_cbranch_scc0 .LBB0_19
	s_cmp_gt_u32 s28, 0x15fff
	v_lshlrev_b32_e32 v2, 1, v16
	s_cbranch_scc0 .LBB0_16
	s_add_i32 s0, s28, 0xfffea000
	s_and_b32 s4, s0, 0xffffff80
	s_bfe_u32 s5, s28, 0x40003
	v_readlane_b32 s36, v249, 4
	s_cmpk_lt_u32 s0, 0x80
	v_readlane_b32 s40, v249, 8
	v_readlane_b32 s41, v249, 9
	v_readlane_b32 s44, v249, 12
	v_readlane_b32 s45, v249, 13
	s_cselect_b32 s0, s41, s45
	s_cselect_b32 s16, s40, s44
	s_lshl_b32 s17, s5, 16
	s_add_u32 s16, s16, s17
	s_addc_u32 s17, s0, 0
	s_lshl_b32 s0, s5, 8
	s_add_i32 s0, s0, s4
	s_lshl_b64 s[4:5], s[0:1], 8
	s_add_u32 s0, s72, s4
	s_addc_u32 s29, s73, s5
	s_and_b32 s30, s18, 64
	s_add_u32 s4, s16, s14
	s_addc_u32 s5, s17, s15
	v_mov_b32_e32 v39, v15
	v_or_b32_e32 v3, s30, v1
	v_lshl_add_u64 v[12:13], s[4:5], 0, v[38:39]
	v_lshlrev_b32_e32 v14, 9, v3
	v_or_b32_e32 v3, s30, v17
	v_lshl_add_u64 v[4:5], v[12:13], 0, v[14:15]
	v_lshlrev_b32_e32 v14, 9, v3
	v_or_b32_e32 v3, s30, v42
	v_lshl_add_u64 v[8:9], v[12:13], 0, v[14:15]
	v_lshlrev_b32_e32 v14, 9, v3
	v_or_b32_e32 v3, s30, v43
	v_lshl_add_u64 v[40:41], v[12:13], 0, v[14:15]
	v_lshlrev_b32_e32 v14, 9, v3
	v_or_b32_e32 v3, s30, v44
	v_lshl_add_u64 v[64:65], v[12:13], 0, v[14:15]
	v_lshlrev_b32_e32 v14, 9, v3
	v_or_b32_e32 v3, s30, v45
	global_load_dwordx4 v[4:7], v[4:5], off nt
	s_nop 0
	global_load_dwordx4 v[8:11], v[8:9], off nt
	s_nop 0
	global_load_dwordx4 v[60:63], v[40:41], off nt
	s_nop 0
	global_load_dwordx4 v[64:67], v[64:65], off nt
	v_lshl_add_u64 v[40:41], v[12:13], 0, v[14:15]
	v_lshlrev_b32_e32 v14, 9, v3
	v_lshl_add_u64 v[72:73], v[12:13], 0, v[14:15]
	global_load_dwordx4 v[68:71], v[40:41], off nt
	s_nop 0
	global_load_dwordx4 v[72:75], v[72:73], off nt
	v_or_b32_e32 v3, s30, v46
	v_lshlrev_b32_e32 v14, 9, v3
	v_lshl_add_u64 v[40:41], v[12:13], 0, v[14:15]
	v_or_b32_e32 v3, s30, v47
	global_load_dwordx4 v[76:79], v[40:41], off nt
	v_lshlrev_b32_e32 v14, 9, v3
	v_lshl_add_u64 v[12:13], v[12:13], 0, v[14:15]
	global_load_dwordx4 v[80:83], v[12:13], off nt
	v_add_u32_e32 v3, 0x18c0, v49
	v_add_u32_e32 v12, 0x18c8, v49
	v_add_u32_e32 v13, 0x1ce0, v49
	v_add_u32_e32 v14, 0x1ce8, v49
	s_lshl_b32 s4, s30, 1
	s_add_u32 s4, s0, s4
	s_addc_u32 s5, s29, 0
	v_readlane_b32 s37, v249, 5
	v_readlane_b32 s38, v249, 6
	v_readlane_b32 s39, v249, 7
	v_readlane_b32 s42, v249, 10
	v_readlane_b32 s43, v249, 11
	v_readlane_b32 s46, v249, 14
	v_readlane_b32 s47, v249, 15
	v_readlane_b32 s48, v249, 16
	v_readlane_b32 s49, v249, 17
	v_readlane_b32 s50, v249, 18
	v_readlane_b32 s51, v249, 19
	s_waitcnt vmcnt(7)
	ds_write2_b32 v49, v4, v5 offset1:1
	ds_write2_b32 v49, v6, v7 offset0:2 offset1:3
	s_waitcnt vmcnt(6)
	ds_write2_b32 v50, v8, v9 offset1:1
	ds_write2_b32 v51, v10, v11 offset1:1
	s_waitcnt vmcnt(5)
	ds_write2_b32 v52, v60, v61 offset1:1
	ds_write2_b32 v53, v62, v63 offset1:1
	s_waitcnt vmcnt(4)
	ds_write2_b32 v54, v64, v65 offset1:1
	ds_write2_b32 v55, v66, v67 offset1:1
	s_waitcnt vmcnt(3)
	ds_write2_b32 v56, v68, v69 offset1:1
	ds_write2_b32 v57, v70, v71 offset1:1
	s_waitcnt vmcnt(2)
	ds_write2_b32 v58, v72, v73 offset1:1
	ds_write2_b32 v59, v74, v75 offset1:1
	s_waitcnt vmcnt(1)
	ds_write2_b32 v3, v76, v77 offset1:1
	ds_write2_b32 v12, v78, v79 offset1:1
	s_waitcnt vmcnt(0)
	ds_write2_b32 v13, v80, v81 offset1:1
	ds_write2_b32 v14, v82, v83 offset1:1
	s_waitcnt lgkmcnt(0)
	ds_read2_b32 v[4:5], v48 offset1:33
	s_waitcnt lgkmcnt(0)
	v_cvt_pk_bf16_f32 v4, v4, v5
	ds_read2_b32 v[6:7], v48 offset0:66 offset1:99
	v_mov_b32_e32 v3, v15
	s_waitcnt lgkmcnt(0)
	v_cvt_pk_bf16_f32 v5, v6, v7
	ds_read2_b32 v[6:7], v48 offset0:132 offset1:165
	v_lshl_add_u64 v[10:11], s[4:5], 0, v[2:3]
	s_waitcnt lgkmcnt(0)
	v_cvt_pk_bf16_f32 v6, v6, v7
	ds_read2_b32 v[8:9], v48 offset0:198 offset1:231
	s_waitcnt lgkmcnt(0)
	v_cvt_pk_bf16_f32 v7, v8, v9
	v_lshl_add_u64 v[12:13], v[10:11], 0, v[30:31]
	ds_read2_b32 v[8:9], v48 offset0:8 offset1:41
	global_store_dwordx4 v[12:13], v[4:7], off
	v_lshl_add_u64 v[12:13], v[10:11], 0, v[32:33]
	s_mov_b64 s[4:5], 0
	s_waitcnt lgkmcnt(0)
	v_cvt_pk_bf16_f32 v4, v8, v9
	ds_read2_b32 v[6:7], v48 offset0:74 offset1:107
	s_waitcnt lgkmcnt(0)
	v_cvt_pk_bf16_f32 v5, v6, v7
	ds_read2_b32 v[6:7], v48 offset0:140 offset1:173
	s_waitcnt lgkmcnt(0)
	v_cvt_pk_bf16_f32 v6, v6, v7
	ds_read2_b32 v[8:9], v48 offset0:206 offset1:239
	s_waitcnt lgkmcnt(0)
	v_cvt_pk_bf16_f32 v7, v8, v9
	ds_read2_b32 v[8:9], v48 offset0:16 offset1:49
	global_store_dwordx4 v[12:13], v[4:7], off
	v_lshl_add_u64 v[12:13], v[10:11], 0, v[34:35]
	s_waitcnt lgkmcnt(0)
	v_cvt_pk_bf16_f32 v4, v8, v9
	ds_read2_b32 v[6:7], v48 offset0:82 offset1:115
	s_waitcnt lgkmcnt(0)
	v_cvt_pk_bf16_f32 v5, v6, v7
	ds_read2_b32 v[6:7], v48 offset0:148 offset1:181
	s_waitcnt lgkmcnt(0)
	v_cvt_pk_bf16_f32 v6, v6, v7
	ds_read2_b32 v[8:9], v48 offset0:214 offset1:247
	s_waitcnt lgkmcnt(0)
	v_cvt_pk_bf16_f32 v7, v8, v9
	ds_read2_b32 v[8:9], v48 offset0:24 offset1:57
	global_store_dwordx4 v[12:13], v[4:7], off
	s_waitcnt lgkmcnt(0)
	s_nop 0
	v_cvt_pk_bf16_f32 v4, v8, v9
	ds_read2_b32 v[6:7], v48 offset0:90 offset1:123
	s_waitcnt lgkmcnt(0)
	v_cvt_pk_bf16_f32 v5, v6, v7
	ds_read2_b32 v[6:7], v48 offset0:156 offset1:189
	s_waitcnt lgkmcnt(0)
	v_cvt_pk_bf16_f32 v6, v6, v7
	ds_read2_b32 v[8:9], v48 offset0:222 offset1:255
	s_waitcnt lgkmcnt(0)
	v_cvt_pk_bf16_f32 v7, v8, v9
	v_lshl_add_u64 v[8:9], v[10:11], 0, v[36:37]
	global_store_dwordx4 v[8:9], v[4:7], off
	s_waitcnt lgkmcnt(0)
.LBB0_16:
	s_andn2_b64 vcc, exec, s[4:5]
	s_cbranch_vccnz .LBB0_18
	s_add_i32 s0, s28, 0xffff2000
	s_and_b32 s16, s0, 0xffffff00
	s_lshr_b32 s0, s0, 10
	s_lshl_b64 s[4:5], s[0:1], 23
	s_add_u32 s0, s58, s4
	s_addc_u32 s4, s59, s5
	s_and_b32 s5, s28, 0x300
	s_lshl_b32 s5, s5, 2
	s_add_u32 s5, s0, s5
	s_addc_u32 s17, s4, 0
	s_mul_hi_u32 s0, s16, 0x1080
	s_mulk_i32 s16, 0x1080
	s_add_u32 s16, s94, s16
	s_addc_u32 s29, s95, s0
	s_and_b32 s0, s9, 0xe0
	s_and_b32 s30, s20, 0x7c0
	s_lshl_b32 s4, s0, 2
	s_add_u32 s4, s5, s4
	s_addc_u32 s5, s17, 0
	v_mov_b32_e32 v39, v15
	v_or_b32_e32 v3, s30, v1
	v_lshl_add_u64 v[12:13], s[4:5], 0, v[38:39]
	v_lshlrev_b32_e32 v14, 12, v3
	v_or_b32_e32 v3, s30, v17
	v_lshl_add_u64 v[4:5], v[12:13], 0, v[14:15]
	v_lshlrev_b32_e32 v14, 12, v3
	v_or_b32_e32 v3, s30, v42
	v_lshl_add_u64 v[8:9], v[12:13], 0, v[14:15]
	v_lshlrev_b32_e32 v14, 12, v3
	v_or_b32_e32 v3, s30, v43
	v_lshl_add_u64 v[40:41], v[12:13], 0, v[14:15]
	v_lshlrev_b32_e32 v14, 12, v3
	v_or_b32_e32 v3, s30, v44
	v_lshl_add_u64 v[64:65], v[12:13], 0, v[14:15]
	v_lshlrev_b32_e32 v14, 12, v3
	v_or_b32_e32 v3, s30, v45
	global_load_dwordx4 v[4:7], v[4:5], off nt
	s_nop 0
	global_load_dwordx4 v[8:11], v[8:9], off nt
	s_nop 0
	global_load_dwordx4 v[60:63], v[40:41], off nt
	s_nop 0
	global_load_dwordx4 v[64:67], v[64:65], off nt
	v_lshl_add_u64 v[40:41], v[12:13], 0, v[14:15]
	v_lshlrev_b32_e32 v14, 12, v3
	v_lshl_add_u64 v[72:73], v[12:13], 0, v[14:15]
	global_load_dwordx4 v[68:71], v[40:41], off nt
	s_nop 0
	global_load_dwordx4 v[72:75], v[72:73], off nt
	v_or_b32_e32 v3, s30, v46
	v_lshlrev_b32_e32 v14, 12, v3
	v_lshl_add_u64 v[40:41], v[12:13], 0, v[14:15]
	v_or_b32_e32 v3, s30, v47
	global_load_dwordx4 v[76:79], v[40:41], off nt
	v_lshlrev_b32_e32 v14, 12, v3
	v_lshl_add_u64 v[12:13], v[12:13], 0, v[14:15]
	global_load_dwordx4 v[80:83], v[12:13], off nt
	v_add_u32_e32 v3, 0x18c0, v49
	v_add_u32_e32 v12, 0x18c8, v49
	v_add_u32_e32 v13, 0x1ce0, v49
	v_add_u32_e32 v14, 0x1ce8, v49
	s_lshl_b32 s4, s30, 1
	s_add_u32 s4, s16, s4
	s_addc_u32 s5, s29, 0
	s_waitcnt vmcnt(7)
	ds_write2_b32 v49, v4, v5 offset1:1
	ds_write2_b32 v49, v6, v7 offset0:2 offset1:3
	s_waitcnt vmcnt(6)
	ds_write2_b32 v50, v8, v9 offset1:1
	ds_write2_b32 v51, v10, v11 offset1:1
	s_waitcnt vmcnt(5)
	ds_write2_b32 v52, v60, v61 offset1:1
	ds_write2_b32 v53, v62, v63 offset1:1
	s_waitcnt vmcnt(4)
	ds_write2_b32 v54, v64, v65 offset1:1
	ds_write2_b32 v55, v66, v67 offset1:1
	s_waitcnt vmcnt(3)
	ds_write2_b32 v56, v68, v69 offset1:1
	ds_write2_b32 v57, v70, v71 offset1:1
	s_waitcnt vmcnt(2)
	ds_write2_b32 v58, v72, v73 offset1:1
	ds_write2_b32 v59, v74, v75 offset1:1
	s_waitcnt vmcnt(1)
	ds_write2_b32 v3, v76, v77 offset1:1
	ds_write2_b32 v12, v78, v79 offset1:1
	s_waitcnt vmcnt(0)
	ds_write2_b32 v13, v80, v81 offset1:1
	ds_write2_b32 v14, v82, v83 offset1:1
	s_waitcnt lgkmcnt(0)
	ds_read2_b32 v[4:5], v48 offset1:33
	s_waitcnt lgkmcnt(0)
	v_cvt_pk_bf16_f32 v4, v4, v5
	ds_read2_b32 v[6:7], v48 offset0:66 offset1:99
	v_or_b32_e32 v10, s0, v1
	s_waitcnt lgkmcnt(0)
	v_cvt_pk_bf16_f32 v5, v6, v7
	ds_read2_b32 v[6:7], v48 offset0:132 offset1:165
	v_mov_b32_e32 v3, v15
	v_mul_u32_u24_e32 v12, 0x840, v10
	s_waitcnt lgkmcnt(0)
	v_cvt_pk_bf16_f32 v6, v6, v7
	ds_read2_b32 v[8:9], v48 offset0:198 offset1:231
	v_lshl_add_u64 v[10:11], s[4:5], 0, v[2:3]
	v_lshlrev_b32_e32 v14, 1, v12
	s_waitcnt lgkmcnt(0)
	v_cvt_pk_bf16_f32 v7, v8, v9
	ds_read2_b32 v[8:9], v48 offset0:8 offset1:41
	v_lshl_add_u64 v[2:3], v[10:11], 0, v[14:15]
	global_store_dwordx4 v[2:3], v[4:7], off
	s_waitcnt lgkmcnt(0)
	v_cvt_pk_bf16_f32 v2, v8, v9
	v_or_b32_e32 v8, s0, v17
	v_mul_u32_u24_e32 v8, 0x840, v8
	ds_read2_b32 v[4:5], v48 offset0:74 offset1:107
	v_lshlrev_b32_e32 v14, 1, v8
	s_waitcnt lgkmcnt(0)
	v_cvt_pk_bf16_f32 v3, v4, v5
	ds_read2_b32 v[4:5], v48 offset0:140 offset1:173
	v_lshl_add_u64 v[8:9], v[10:11], 0, v[14:15]
	s_waitcnt lgkmcnt(0)
	v_cvt_pk_bf16_f32 v4, v4, v5
	ds_read2_b32 v[6:7], v48 offset0:206 offset1:239
	s_waitcnt lgkmcnt(0)
	v_cvt_pk_bf16_f32 v5, v6, v7
	global_store_dwordx4 v[8:9], v[2:5], off
	v_or_b32_e32 v8, s0, v42
	ds_read2_b32 v[6:7], v48 offset0:16 offset1:49
	s_waitcnt lgkmcnt(0)
	v_cvt_pk_bf16_f32 v2, v6, v7
	ds_read2_b32 v[4:5], v48 offset0:82 offset1:115
	v_mul_u32_u24_e32 v8, 0x840, v8
	s_waitcnt lgkmcnt(0)
	v_cvt_pk_bf16_f32 v3, v4, v5
	ds_read2_b32 v[4:5], v48 offset0:148 offset1:181
	v_lshlrev_b32_e32 v14, 1, v8
	s_waitcnt lgkmcnt(0)
	v_cvt_pk_bf16_f32 v4, v4, v5
	ds_read2_b32 v[6:7], v48 offset0:214 offset1:247
	s_waitcnt lgkmcnt(0)
	v_cvt_pk_bf16_f32 v5, v6, v7
	v_lshl_add_u64 v[8:9], v[10:11], 0, v[14:15]
	ds_read2_b32 v[6:7], v48 offset0:24 offset1:57
	global_store_dwordx4 v[8:9], v[2:5], off
	s_waitcnt lgkmcnt(0)
	s_nop 0
	v_cvt_pk_bf16_f32 v2, v6, v7
	ds_read2_b32 v[4:5], v48 offset0:90 offset1:123
	s_waitcnt lgkmcnt(0)
	v_cvt_pk_bf16_f32 v3, v4, v5
	ds_read2_b32 v[4:5], v48 offset0:156 offset1:189
	s_waitcnt lgkmcnt(0)
	v_cvt_pk_bf16_f32 v4, v4, v5
	v_or_b32_e32 v5, s0, v43
	v_mul_u32_u24_e32 v5, 0x840, v5
	ds_read2_b32 v[6:7], v48 offset0:222 offset1:255
	v_lshlrev_b32_e32 v14, 1, v5
	s_waitcnt lgkmcnt(0)
	v_cvt_pk_bf16_f32 v5, v6, v7
	v_lshl_add_u64 v[6:7], v[10:11], 0, v[14:15]
	global_store_dwordx4 v[6:7], v[2:5], off
	s_waitcnt lgkmcnt(0)

.LBB0_19:
	s_andn2_b64 vcc, exec, s[4:5]
	s_cbranch_vccnz .LBB0_38
	s_add_i32 s0, s28, 0xa000
	s_lshr_b32 s0, s0, 3
	s_and_b32 s17, s0, 0x1fc0
	s_and_b32 s16, s9, 0x3fe0
	s_lshl_b32 s0, s16, 2
	v_or_b32_e32 v6, s17, v1
	v_lshl_add_u64 v[40:41], v[18:19], 0, s[0:1]
	v_lshlrev_b32_e32 v14, 16, v6
	v_lshl_add_u64 v[2:3], v[40:41], 0, v[14:15]
	global_load_dwordx4 v[2:5], v[2:3], off nt
	v_cndmask_b32_e64 v7, 0, 1, s[12:13]
	v_cmp_ne_u32_e64 s[4:5], 1, v7
	s_andn2_b64 vcc, exec, s[12:13]
	s_cbranch_vccnz .LBB0_22
	v_readlane_b32 s36, v249, 20
	v_lshlrev_b32_e32 v6, 2, v6
	v_readlane_b32 s46, v249, 30
	v_readlane_b32 s47, v249, 31
	v_readlane_b32 s37, v249, 21
	v_readlane_b32 s38, v249, 22
	v_readlane_b32 s39, v249, 23
	v_readlane_b32 s40, v249, 24
	v_readlane_b32 s41, v249, 25
	global_load_dword v6, v6, s[46:47]
	v_readlane_b32 s42, v249, 26
	v_readlane_b32 s43, v249, 27
	v_readlane_b32 s44, v249, 28
	v_readlane_b32 s45, v249, 29
	v_readlane_b32 s48, v249, 32
	v_readlane_b32 s49, v249, 33
	v_readlane_b32 s50, v249, 34
	v_readlane_b32 s51, v249, 35
	s_waitcnt vmcnt(0)
	v_pk_mul_f32 v[4:5], v[4:5], v[6:7] op_sel_hi:[1,0]
	v_pk_mul_f32 v[2:3], v[2:3], v[6:7] op_sel_hi:[1,0]
.LBB0_22:
	v_or_b32_sdwa v14, s17, v17 dst_sel:WORD_1 dst_unused:UNUSED_PAD src0_sel:DWORD src1_sel:DWORD
	s_and_b64 vcc, exec, s[4:5]
	v_lshl_add_u64 v[6:7], v[40:41], 0, v[14:15]
	global_load_dwordx4 v[6:9], v[6:7], off nt
	v_add_lshl_u32 v39, s17, v1, 2
	s_waitcnt vmcnt(1)
	ds_write2_b32 v49, v2, v3 offset1:1
	ds_write2_b32 v49, v4, v5 offset0:2 offset1:3
	s_cbranch_vccnz .LBB0_24
	v_readlane_b32 s36, v249, 20
	v_readlane_b32 s46, v249, 30
	v_readlane_b32 s47, v249, 31
	v_readlane_b32 s37, v249, 21
	v_readlane_b32 s38, v249, 22
	v_readlane_b32 s39, v249, 23
	v_readlane_b32 s40, v249, 24
	v_readlane_b32 s41, v249, 25
	global_load_dword v2, v39, s[46:47] offset:32
	v_readlane_b32 s42, v249, 26
	v_readlane_b32 s43, v249, 27
	v_readlane_b32 s44, v249, 28
	v_readlane_b32 s45, v249, 29
	v_readlane_b32 s48, v249, 32
	v_readlane_b32 s49, v249, 33
	v_readlane_b32 s50, v249, 34
	v_readlane_b32 s51, v249, 35
	s_waitcnt vmcnt(0)
	v_pk_mul_f32 v[8:9], v[8:9], v[2:3] op_sel_hi:[1,0]
	v_pk_mul_f32 v[6:7], v[6:7], v[2:3] op_sel_hi:[1,0]
.LBB0_24:
	v_or_b32_sdwa v14, s17, v42 dst_sel:WORD_1 dst_unused:UNUSED_PAD src0_sel:DWORD src1_sel:DWORD
	s_and_b64 vcc, exec, s[4:5]
	v_lshl_add_u64 v[2:3], v[40:41], 0, v[14:15]
	global_load_dwordx4 v[2:5], v[2:3], off nt
	s_waitcnt vmcnt(1)
	ds_write2_b32 v50, v6, v7 offset1:1
	ds_write2_b32 v51, v8, v9 offset1:1
	s_cbranch_vccnz .LBB0_26
	v_readlane_b32 s36, v249, 20
	v_readlane_b32 s46, v249, 30
	v_readlane_b32 s47, v249, 31
	v_readlane_b32 s37, v249, 21
	v_readlane_b32 s38, v249, 22
	v_readlane_b32 s39, v249, 23
	v_readlane_b32 s40, v249, 24
	v_readlane_b32 s41, v249, 25
	global_load_dword v6, v39, s[46:47] offset:64
	v_readlane_b32 s42, v249, 26
	v_readlane_b32 s43, v249, 27
	v_readlane_b32 s44, v249, 28
	v_readlane_b32 s45, v249, 29
	v_readlane_b32 s48, v249, 32
	v_readlane_b32 s49, v249, 33
	v_readlane_b32 s50, v249, 34
	v_readlane_b32 s51, v249, 35
	s_waitcnt vmcnt(0)
	v_pk_mul_f32 v[4:5], v[4:5], v[6:7] op_sel_hi:[1,0]
	v_pk_mul_f32 v[2:3], v[2:3], v[6:7] op_sel_hi:[1,0]
.LBB0_26:
	v_or_b32_sdwa v14, s17, v43 dst_sel:WORD_1 dst_unused:UNUSED_PAD src0_sel:DWORD src1_sel:DWORD
	s_and_b64 vcc, exec, s[4:5]
	v_lshl_add_u64 v[6:7], v[40:41], 0, v[14:15]
	global_load_dwordx4 v[6:9], v[6:7], off nt
	s_waitcnt vmcnt(1)
	ds_write2_b32 v52, v2, v3 offset1:1
	ds_write2_b32 v53, v4, v5 offset1:1
	s_cbranch_vccnz .LBB0_28
	v_readlane_b32 s36, v249, 20
	v_readlane_b32 s46, v249, 30
	v_readlane_b32 s47, v249, 31
	v_readlane_b32 s37, v249, 21
	v_readlane_b32 s38, v249, 22
	v_readlane_b32 s39, v249, 23
	v_readlane_b32 s40, v249, 24
	v_readlane_b32 s41, v249, 25
	global_load_dword v2, v39, s[46:47] offset:96
	v_readlane_b32 s42, v249, 26
	v_readlane_b32 s43, v249, 27
	v_readlane_b32 s44, v249, 28
	v_readlane_b32 s45, v249, 29
	v_readlane_b32 s48, v249, 32
	v_readlane_b32 s49, v249, 33
	v_readlane_b32 s50, v249, 34
	v_readlane_b32 s51, v249, 35
	s_waitcnt vmcnt(0)
	v_pk_mul_f32 v[8:9], v[8:9], v[2:3] op_sel_hi:[1,0]
	v_pk_mul_f32 v[6:7], v[6:7], v[2:3] op_sel_hi:[1,0]
.LBB0_28:
	v_or_b32_sdwa v14, s17, v44 dst_sel:WORD_1 dst_unused:UNUSED_PAD src0_sel:DWORD src1_sel:DWORD
	s_and_b64 vcc, exec, s[4:5]
	v_lshl_add_u64 v[2:3], v[40:41], 0, v[14:15]
	global_load_dwordx4 v[2:5], v[2:3], off nt
	s_waitcnt vmcnt(1)
	ds_write2_b32 v54, v6, v7 offset1:1
	ds_write2_b32 v55, v8, v9 offset1:1
	s_cbranch_vccnz .LBB0_30
	v_readlane_b32 s36, v249, 20
	v_readlane_b32 s46, v249, 30
	v_readlane_b32 s47, v249, 31
	v_readlane_b32 s37, v249, 21
	v_readlane_b32 s38, v249, 22
	v_readlane_b32 s39, v249, 23
	v_readlane_b32 s40, v249, 24
	v_readlane_b32 s41, v249, 25
	global_load_dword v6, v39, s[46:47] offset:128
	v_readlane_b32 s42, v249, 26
	v_readlane_b32 s43, v249, 27
	v_readlane_b32 s44, v249, 28
	v_readlane_b32 s45, v249, 29
	v_readlane_b32 s48, v249, 32
	v_readlane_b32 s49, v249, 33
	v_readlane_b32 s50, v249, 34
	v_readlane_b32 s51, v249, 35
	s_waitcnt vmcnt(0)
	v_pk_mul_f32 v[4:5], v[4:5], v[6:7] op_sel_hi:[1,0]
	v_pk_mul_f32 v[2:3], v[2:3], v[6:7] op_sel_hi:[1,0]
.LBB0_30:
	v_or_b32_sdwa v14, s17, v45 dst_sel:WORD_1 dst_unused:UNUSED_PAD src0_sel:DWORD src1_sel:DWORD
	s_and_b64 vcc, exec, s[4:5]
	v_lshl_add_u64 v[6:7], v[40:41], 0, v[14:15]
	global_load_dwordx4 v[10:13], v[6:7], off nt
	s_waitcnt vmcnt(1)
	ds_write2_b32 v56, v2, v3 offset1:1
	ds_write2_b32 v57, v4, v5 offset1:1
	s_cbranch_vccnz .LBB0_32
	v_readlane_b32 s36, v249, 20
	v_readlane_b32 s46, v249, 30
	v_readlane_b32 s47, v249, 31
	v_readlane_b32 s37, v249, 21
	v_readlane_b32 s38, v249, 22
	v_readlane_b32 s39, v249, 23
	v_readlane_b32 s40, v249, 24
	v_readlane_b32 s41, v249, 25
	global_load_dword v2, v39, s[46:47] offset:160
	v_readlane_b32 s42, v249, 26
	v_readlane_b32 s43, v249, 27
	v_readlane_b32 s44, v249, 28
	v_readlane_b32 s45, v249, 29
	v_readlane_b32 s48, v249, 32
	v_readlane_b32 s49, v249, 33
	v_readlane_b32 s50, v249, 34
	v_readlane_b32 s51, v249, 35
	s_waitcnt vmcnt(0)
	v_pk_mul_f32 v[12:13], v[12:13], v[2:3] op_sel_hi:[1,0]
	v_pk_mul_f32 v[10:11], v[10:11], v[2:3] op_sel_hi:[1,0]
.LBB0_32:
	v_or_b32_sdwa v14, s17, v46 dst_sel:WORD_1 dst_unused:UNUSED_PAD src0_sel:DWORD src1_sel:DWORD
	s_and_b64 vcc, exec, s[4:5]
	v_lshl_add_u64 v[2:3], v[40:41], 0, v[14:15]
	global_load_dwordx4 v[6:9], v[2:3], off nt
	s_waitcnt vmcnt(1)
	ds_write2_b32 v58, v10, v11 offset1:1
	ds_write2_b32 v59, v12, v13 offset1:1
	s_cbranch_vccnz .LBB0_34
	v_readlane_b32 s36, v249, 20
	v_readlane_b32 s46, v249, 30
	v_readlane_b32 s47, v249, 31
	v_readlane_b32 s37, v249, 21
	v_readlane_b32 s38, v249, 22
	v_readlane_b32 s39, v249, 23
	v_readlane_b32 s40, v249, 24
	v_readlane_b32 s41, v249, 25
	global_load_dword v2, v39, s[46:47] offset:192
	v_readlane_b32 s42, v249, 26
	v_readlane_b32 s43, v249, 27
	v_readlane_b32 s44, v249, 28
	v_readlane_b32 s45, v249, 29
	v_readlane_b32 s48, v249, 32
	v_readlane_b32 s49, v249, 33
	v_readlane_b32 s50, v249, 34
	v_readlane_b32 s51, v249, 35
	s_waitcnt vmcnt(0)
	v_pk_mul_f32 v[8:9], v[8:9], v[2:3] op_sel_hi:[1,0]
	v_pk_mul_f32 v[6:7], v[6:7], v[2:3] op_sel_hi:[1,0]
.LBB0_34:
	v_or_b32_sdwa v14, s17, v47 dst_sel:WORD_1 dst_unused:UNUSED_PAD src0_sel:DWORD src1_sel:DWORD
	v_add_u32_e32 v10, 0x18c0, v49
	v_lshl_add_u64 v[2:3], v[40:41], 0, v[14:15]
	global_load_dwordx4 v[2:5], v[2:3], off nt
	s_waitcnt vmcnt(1)
	ds_write2_b32 v10, v6, v7 offset1:1
	v_add_u32_e32 v6, 0x18c8, v49
	s_and_b64 vcc, exec, s[12:13]
	ds_write2_b32 v6, v8, v9 offset1:1
	s_cbranch_vccz .LBB0_44
	v_readlane_b32 s36, v249, 20
	v_readlane_b32 s46, v249, 30
	v_readlane_b32 s47, v249, 31
	v_readlane_b32 s37, v249, 21
	v_readlane_b32 s38, v249, 22
	v_readlane_b32 s39, v249, 23
	v_readlane_b32 s40, v249, 24
	v_readlane_b32 s41, v249, 25
	global_load_dword v6, v39, s[46:47] offset:224
	v_readlane_b32 s42, v249, 26
	v_readlane_b32 s43, v249, 27
	v_readlane_b32 s44, v249, 28
	v_readlane_b32 s45, v249, 29
	v_readlane_b32 s48, v249, 32
	v_readlane_b32 s49, v249, 33
	v_readlane_b32 s50, v249, 34
	v_readlane_b32 s51, v249, 35
	s_waitcnt vmcnt(0)
	v_pk_mul_f32 v[8:9], v[4:5], v[6:7] op_sel_hi:[1,0]
	v_pk_mul_f32 v[6:7], v[2:3], v[6:7] op_sel_hi:[1,0]
	s_cbranch_execnz .LBB0_37

.LBB0_39:
	s_andn2_b64 vcc, exec, s[4:5]
	s_cbranch_vccnz .LBB0_41
	s_add_i32 s0, s28, 0xc000
	s_lshr_b32 s0, s0, 1
	s_and_b32 s5, s0, 0x7fc0
	s_and_b32 s4, s9, 0xfe0
	s_lshl_b32 s0, s4, 2
	v_or_b32_e32 v2, s5, v1
	v_lshl_add_u64 v[40:41], v[22:23], 0, s[0:1]
	v_lshlrev_b32_e32 v14, 14, v2
	v_or_b32_e32 v4, s5, v17
	v_lshl_add_u64 v[2:3], v[40:41], 0, v[14:15]
	v_lshlrev_b32_e32 v14, 14, v4
	v_or_b32_e32 v10, s5, v42
	v_lshl_add_u64 v[6:7], v[40:41], 0, v[14:15]
	v_lshlrev_b32_e32 v14, 14, v10
	v_or_b32_e32 v12, s5, v43
	v_lshl_add_u64 v[10:11], v[40:41], 0, v[14:15]
	v_lshlrev_b32_e32 v14, 14, v12
	v_lshl_add_u64 v[60:61], v[40:41], 0, v[14:15]
	v_or_b32_e32 v14, s5, v44
	v_lshlrev_b32_e32 v14, 14, v14
	v_lshl_add_u64 v[64:65], v[40:41], 0, v[14:15]
	v_or_b32_e32 v14, s5, v45
	v_lshlrev_b32_e32 v14, 14, v14
	v_lshl_add_u64 v[68:69], v[40:41], 0, v[14:15]
	global_load_dwordx4 v[2:5], v[2:3], off nt
	s_nop 0
	global_load_dwordx4 v[6:9], v[6:7], off nt
	s_nop 0
	global_load_dwordx4 v[10:13], v[10:11], off nt
	s_nop 0
	global_load_dwordx4 v[60:63], v[60:61], off nt
	s_nop 0
	global_load_dwordx4 v[64:67], v[64:65], off nt
	s_nop 0
	global_load_dwordx4 v[68:71], v[68:69], off nt
	v_or_b32_e32 v14, s5, v46
	v_lshlrev_b32_e32 v14, 14, v14
	v_lshl_add_u64 v[72:73], v[40:41], 0, v[14:15]
	v_or_b32_e32 v14, s5, v47
	global_load_dwordx4 v[72:75], v[72:73], off nt
	v_lshlrev_b32_e32 v14, 14, v14
	v_lshl_add_u64 v[40:41], v[40:41], 0, v[14:15]
	global_load_dwordx4 v[76:79], v[40:41], off nt
	v_add_u32_e32 v14, 0x18c0, v49
	v_add_u32_e32 v39, 0x18c8, v49
	v_add_u32_e32 v40, 0x1ce0, v49
	v_add_u32_e32 v41, 0x1ce8, v49
	s_lshl_b32 s0, s5, 1
	s_waitcnt vmcnt(7)
	ds_write2_b32 v49, v2, v3 offset1:1
	ds_write2_b32 v49, v4, v5 offset0:2 offset1:3
	s_waitcnt vmcnt(6)
	ds_write2_b32 v50, v6, v7 offset1:1
	ds_write2_b32 v51, v8, v9 offset1:1
	s_waitcnt vmcnt(5)
	ds_write2_b32 v52, v10, v11 offset1:1
	ds_write2_b32 v53, v12, v13 offset1:1
	s_waitcnt vmcnt(4)
	ds_write2_b32 v54, v60, v61 offset1:1
	ds_write2_b32 v55, v62, v63 offset1:1
	s_waitcnt vmcnt(3)
	ds_write2_b32 v56, v64, v65 offset1:1
	ds_write2_b32 v57, v66, v67 offset1:1
	s_waitcnt vmcnt(2)
	ds_write2_b32 v58, v68, v69 offset1:1
	ds_write2_b32 v59, v70, v71 offset1:1
	s_waitcnt vmcnt(1)
	ds_write2_b32 v14, v72, v73 offset1:1
	ds_write2_b32 v39, v74, v75 offset1:1
	s_waitcnt vmcnt(0)
	ds_write2_b32 v40, v76, v77 offset1:1
	ds_write2_b32 v41, v78, v79 offset1:1
	s_waitcnt lgkmcnt(0)
	ds_read2_b32 v[2:3], v48 offset1:33
	s_waitcnt lgkmcnt(0)
	v_cvt_pk_bf16_f32 v2, v2, v3
	ds_read2_b32 v[4:5], v48 offset0:66 offset1:99
	v_or_b32_e32 v10, s4, v1
	s_waitcnt lgkmcnt(0)
	v_cvt_pk_bf16_f32 v3, v4, v5
	ds_read2_b32 v[4:5], v48 offset0:132 offset1:165
	v_lshl_add_u64 v[8:9], v[24:25], 0, s[0:1]
	v_lshlrev_b32_e32 v14, 13, v10
	s_waitcnt lgkmcnt(0)
	v_cvt_pk_bf16_f32 v4, v4, v5
	ds_read2_b32 v[6:7], v48 offset0:198 offset1:231
	s_waitcnt lgkmcnt(0)
	v_cvt_pk_bf16_f32 v5, v6, v7
	v_lshl_add_u64 v[10:11], v[8:9], 0, v[14:15]
	ds_read2_b32 v[6:7], v48 offset0:8 offset1:41
	global_store_dwordx4 v[10:11], v[2:5], off
	v_or_b32_e32 v10, s4, v17
	v_lshlrev_b32_e32 v14, 13, v10
	s_waitcnt lgkmcnt(0)
	v_cvt_pk_bf16_f32 v2, v6, v7
	ds_read2_b32 v[4:5], v48 offset0:74 offset1:107
	s_waitcnt lgkmcnt(0)
	v_cvt_pk_bf16_f32 v3, v4, v5
	ds_read2_b32 v[4:5], v48 offset0:140 offset1:173
	s_waitcnt lgkmcnt(0)
	v_cvt_pk_bf16_f32 v4, v4, v5
	ds_read2_b32 v[6:7], v48 offset0:206 offset1:239
	s_waitcnt lgkmcnt(0)
	v_cvt_pk_bf16_f32 v5, v6, v7
	v_lshl_add_u64 v[10:11], v[8:9], 0, v[14:15]
	ds_read2_b32 v[6:7], v48 offset0:16 offset1:49
	global_store_dwordx4 v[10:11], v[2:5], off
	v_or_b32_e32 v10, s4, v42
	v_lshlrev_b32_e32 v14, 13, v10
	s_waitcnt lgkmcnt(0)
	v_cvt_pk_bf16_f32 v2, v6, v7
	ds_read2_b32 v[4:5], v48 offset0:82 offset1:115
	s_waitcnt lgkmcnt(0)
	v_cvt_pk_bf16_f32 v3, v4, v5
	ds_read2_b32 v[4:5], v48 offset0:148 offset1:181
	s_waitcnt lgkmcnt(0)
	v_cvt_pk_bf16_f32 v4, v4, v5
	ds_read2_b32 v[6:7], v48 offset0:214 offset1:247
	s_waitcnt lgkmcnt(0)
	v_cvt_pk_bf16_f32 v5, v6, v7
	v_lshl_add_u64 v[10:11], v[8:9], 0, v[14:15]
	ds_read2_b32 v[6:7], v48 offset0:24 offset1:57
	global_store_dwordx4 v[10:11], v[2:5], off
	s_waitcnt lgkmcnt(0)
	s_nop 0
	v_cvt_pk_bf16_f32 v2, v6, v7
	ds_read2_b32 v[4:5], v48 offset0:90 offset1:123
	s_waitcnt lgkmcnt(0)
	v_cvt_pk_bf16_f32 v3, v4, v5
	ds_read2_b32 v[4:5], v48 offset0:156 offset1:189
	s_waitcnt lgkmcnt(0)
	v_cvt_pk_bf16_f32 v4, v4, v5
	v_or_b32_e32 v5, s4, v43
	ds_read2_b32 v[6:7], v48 offset0:222 offset1:255
	v_lshlrev_b32_e32 v14, 13, v5
	s_waitcnt lgkmcnt(0)
	v_cvt_pk_bf16_f32 v5, v6, v7
	v_lshl_add_u64 v[6:7], v[8:9], 0, v[14:15]
	global_store_dwordx4 v[6:7], v[2:5], off
	s_waitcnt lgkmcnt(0)

.LBB0_42:
	s_andn2_b64 vcc, exec, s[4:5]
	s_cbranch_vccnz .LBB0_10
	s_ashr_i32 s0, s28, 31
	s_lshr_b32 s0, s0, 24
	s_add_i32 s0, s28, s0
	s_ashr_i32 s0, s0, 8
	s_lshl_b32 s16, s0, 6
	s_lshl_b32 s0, s0, 13
	s_sub_i32 s4, s9, s0
	v_or_b32_e32 v2, s16, v1
	v_or_b32_e32 v4, s16, v17
	v_or_b32_e32 v10, s16, v42
	v_or_b32_e32 v12, s16, v43
	v_or_b32_e32 v64, s16, v44
	v_or_b32_e32 v66, s16, v45
	s_ashr_i32 s5, s4, 31
	v_ashrrev_i32_e32 v3, 31, v2
	v_ashrrev_i32_e32 v5, 31, v4
	v_ashrrev_i32_e32 v11, 31, v10
	v_ashrrev_i32_e32 v13, 31, v12
	v_ashrrev_i32_e32 v65, 31, v64
	v_ashrrev_i32_e32 v67, 31, v66
	v_lshl_add_u64 v[40:41], s[4:5], 2, v[26:27]
	v_lshlrev_b64 v[2:3], 15, v[2:3]
	v_lshlrev_b64 v[4:5], 15, v[4:5]
	v_lshlrev_b64 v[10:11], 15, v[10:11]
	v_lshlrev_b64 v[12:13], 15, v[12:13]
	v_lshlrev_b64 v[64:65], 15, v[64:65]
	v_lshlrev_b64 v[66:67], 15, v[66:67]
	v_lshl_add_u64 v[2:3], v[40:41], 0, v[2:3]
	v_lshl_add_u64 v[6:7], v[40:41], 0, v[4:5]
	v_lshl_add_u64 v[10:11], v[40:41], 0, v[10:11]
	v_lshl_add_u64 v[60:61], v[40:41], 0, v[12:13]
	v_lshl_add_u64 v[64:65], v[40:41], 0, v[64:65]
	v_lshl_add_u64 v[68:69], v[40:41], 0, v[66:67]
	global_load_dwordx4 v[2:5], v[2:3], off nt
	s_nop 0
	global_load_dwordx4 v[6:9], v[6:7], off nt
	s_nop 0
	global_load_dwordx4 v[10:13], v[10:11], off nt
	s_nop 0
	global_load_dwordx4 v[60:63], v[60:61], off nt
	s_nop 0
	global_load_dwordx4 v[64:67], v[64:65], off nt
	s_nop 0
	global_load_dwordx4 v[68:71], v[68:69], off nt
	v_or_b32_e32 v72, s16, v46
	v_ashrrev_i32_e32 v73, 31, v72
	v_lshlrev_b64 v[72:73], 15, v[72:73]
	v_or_b32_e32 v76, s16, v47
	v_lshl_add_u64 v[72:73], v[40:41], 0, v[72:73]
	v_ashrrev_i32_e32 v77, 31, v76
	global_load_dwordx4 v[72:75], v[72:73], off nt
	v_lshlrev_b64 v[76:77], 15, v[76:77]
	v_lshl_add_u64 v[40:41], v[40:41], 0, v[76:77]
	global_load_dwordx4 v[76:79], v[40:41], off nt
	v_add_u32_e32 v14, 0x18c0, v49
	v_add_u32_e32 v39, 0x18c8, v49
	v_add_u32_e32 v40, 0x1ce0, v49
	v_add_u32_e32 v41, 0x1ce8, v49
	s_ashr_i32 s17, s16, 31
	s_waitcnt vmcnt(7)
	ds_write2_b32 v49, v2, v3 offset1:1
	ds_write2_b32 v49, v4, v5 offset0:2 offset1:3
	s_waitcnt vmcnt(6)
	ds_write2_b32 v50, v6, v7 offset1:1
	ds_write2_b32 v51, v8, v9 offset1:1
	s_waitcnt vmcnt(5)
	ds_write2_b32 v52, v10, v11 offset1:1
	ds_write2_b32 v53, v12, v13 offset1:1
	s_waitcnt vmcnt(4)
	ds_write2_b32 v54, v60, v61 offset1:1
	ds_write2_b32 v55, v62, v63 offset1:1
	s_waitcnt vmcnt(3)
	ds_write2_b32 v56, v64, v65 offset1:1
	ds_write2_b32 v57, v66, v67 offset1:1
	s_waitcnt vmcnt(2)
	ds_write2_b32 v58, v68, v69 offset1:1
	ds_write2_b32 v59, v70, v71 offset1:1
	s_waitcnt vmcnt(1)
	ds_write2_b32 v14, v72, v73 offset1:1
	ds_write2_b32 v39, v74, v75 offset1:1
	s_waitcnt vmcnt(0)
	ds_write2_b32 v40, v76, v77 offset1:1
	ds_write2_b32 v41, v78, v79 offset1:1
	s_waitcnt lgkmcnt(0)
	v_add_u32_e32 v10, s4, v1
	ds_read2_b32 v[2:3], v48 offset1:33
	v_ashrrev_i32_e32 v11, 31, v10
	s_waitcnt lgkmcnt(0)
	v_cvt_pk_bf16_f32 v2, v2, v3
	ds_read2_b32 v[4:5], v48 offset0:66 offset1:99
	v_lshl_add_u64 v[8:9], s[16:17], 1, v[28:29]
	v_lshlrev_b64 v[12:13], 13, v[10:11]
	s_waitcnt lgkmcnt(0)
	v_cvt_pk_bf16_f32 v3, v4, v5
	ds_read2_b32 v[4:5], v48 offset0:132 offset1:165
	v_lshl_add_u64 v[12:13], v[8:9], 0, v[12:13]
	s_waitcnt lgkmcnt(0)
	v_cvt_pk_bf16_f32 v4, v4, v5
	ds_read2_b32 v[6:7], v48 offset0:198 offset1:231
	s_waitcnt lgkmcnt(0)
	v_cvt_pk_bf16_f32 v5, v6, v7
	global_store_dwordx4 v[12:13], v[2:5], off
	v_add_u32_e32 v12, 8, v10
	v_ashrrev_i32_e32 v13, 31, v12
	ds_read2_b32 v[6:7], v48 offset0:8 offset1:41
	s_waitcnt lgkmcnt(0)
	v_cvt_pk_bf16_f32 v2, v6, v7
	ds_read2_b32 v[4:5], v48 offset0:74 offset1:107
	v_lshlrev_b64 v[12:13], 13, v[12:13]
	s_waitcnt lgkmcnt(0)
	v_cvt_pk_bf16_f32 v3, v4, v5
	ds_read2_b32 v[4:5], v48 offset0:140 offset1:173
	v_lshl_add_u64 v[12:13], v[8:9], 0, v[12:13]
	s_waitcnt lgkmcnt(0)
	v_cvt_pk_bf16_f32 v4, v4, v5
	ds_read2_b32 v[6:7], v48 offset0:206 offset1:239
	s_waitcnt lgkmcnt(0)
	v_cvt_pk_bf16_f32 v5, v6, v7
	global_store_dwordx4 v[12:13], v[2:5], off
	v_add_u32_e32 v12, 16, v10
	ds_read2_b32 v[6:7], v48 offset0:16 offset1:49
	s_waitcnt lgkmcnt(0)
	v_cvt_pk_bf16_f32 v2, v6, v7
	ds_read2_b32 v[4:5], v48 offset0:82 offset1:115
	v_ashrrev_i32_e32 v13, 31, v12
	s_waitcnt lgkmcnt(0)
	v_cvt_pk_bf16_f32 v3, v4, v5
	ds_read2_b32 v[4:5], v48 offset0:148 offset1:181
	v_lshlrev_b64 v[12:13], 13, v[12:13]
	s_waitcnt lgkmcnt(0)
	v_cvt_pk_bf16_f32 v4, v4, v5
	ds_read2_b32 v[6:7], v48 offset0:214 offset1:247
	s_waitcnt lgkmcnt(0)
	v_cvt_pk_bf16_f32 v5, v6, v7
	v_lshl_add_u64 v[12:13], v[8:9], 0, v[12:13]
	ds_read2_b32 v[6:7], v48 offset0:24 offset1:57
	global_store_dwordx4 v[12:13], v[2:5], off
	v_add_u32_e32 v10, 24, v10
	v_ashrrev_i32_e32 v11, 31, v10
	s_waitcnt lgkmcnt(0)
	v_cvt_pk_bf16_f32 v2, v6, v7
	ds_read2_b32 v[4:5], v48 offset0:90 offset1:123
	s_waitcnt lgkmcnt(0)
	v_cvt_pk_bf16_f32 v3, v4, v5
	ds_read2_b32 v[4:5], v48 offset0:156 offset1:189
	s_waitcnt lgkmcnt(0)
	v_cvt_pk_bf16_f32 v4, v4, v5
	ds_read2_b32 v[6:7], v48 offset0:222 offset1:255
	v_lshlrev_b64 v[10:11], 13, v[10:11]
	s_waitcnt lgkmcnt(0)
	v_cvt_pk_bf16_f32 v5, v6, v7
	v_lshl_add_u64 v[6:7], v[8:9], 0, v[10:11]
	global_store_dwordx4 v[6:7], v[2:5], off
	s_waitcnt lgkmcnt(0)
	s_branch .LBB0_10

.LBB0_47:
	v_lshl_add_u64 v[2:3], s[0:1], 0, v[66:67]
	v_add_co_u32_e32 v4, vcc, s21, v2
	global_load_dwordx4 v[58:61], v66, s[0:1]
	global_load_dwordx4 v[46:49], v66, s[0:1] offset:1024
	global_load_dwordx4 v[38:41], v66, s[0:1] offset:2048
	global_load_dwordx4 v[26:29], v66, s[0:1] offset:3072
	v_addc_co_u32_e32 v5, vcc, 0, v3, vcc
	global_load_dwordx4 v[18:21], v[4:5], off offset:-4096 nt
	v_add_co_u32_e32 v6, vcc, s20, v2
	s_waitcnt vmcnt(4)
	v_mul_f32_e32 v103, v59, v59
	v_addc_co_u32_e32 v7, vcc, 0, v3, vcc
	global_load_dwordx4 v[14:17], v[6:7], off offset:1024 nt
	global_load_dwordx4 v[10:13], v[6:7], off offset:2048 nt
	s_nop 0
	global_load_dwordx4 v[6:9], v[6:7], off offset:3072 nt
	s_nop 0
	global_load_dwordx4 v[62:65], v[4:5], off nt
	global_load_dwordx4 v[54:57], v[4:5], off offset:1024 nt
	global_load_dwordx4 v[50:53], v[4:5], off offset:2048 nt
	global_load_dwordx4 v[42:45], v[4:5], off offset:3072 nt
	v_add_co_u32_e32 v22, vcc, s28, v2
	v_mul_f32_e32 v104, v61, v61
	s_nop 0
	v_addc_co_u32_e32 v23, vcc, 0, v3, vcc
	global_load_dwordx4 v[30:33], v[22:23], off nt
	global_load_dwordx4 v[34:37], v[22:23], off offset:1024 nt
	global_load_dwordx4 v[2:5], v[22:23], off offset:3072 nt
	s_nop 0
	global_load_dwordx4 v[22:25], v[22:23], off offset:2048 nt
	s_waitcnt vmcnt(14)
	v_mul_f32_e32 v105, v47, v47
	v_mul_f32_e32 v106, v49, v49
	s_waitcnt vmcnt(13)
	v_mul_f32_e32 v107, v39, v39
	v_mul_f32_e32 v108, v41, v41
	v_fmac_f32_e32 v103, v58, v58
	v_fmac_f32_e32 v104, v60, v60
	v_fmac_f32_e32 v105, v46, v46
	v_fmac_f32_e32 v106, v48, v48
	s_waitcnt vmcnt(12)
	v_mul_f32_e32 v109, v27, v27
	v_mul_f32_e32 v110, v29, v29
	v_fmac_f32_e32 v107, v38, v38
	v_fmac_f32_e32 v108, v40, v40
	v_add_f32_e32 v103, v103, v104
	v_add_f32_e32 v104, v105, v106
	v_fmac_f32_e32 v109, v26, v26
	v_fmac_f32_e32 v110, v28, v28
	v_add_f32_e32 v105, v107, v108
	s_waitcnt vmcnt(11)
	v_mul_f32_e32 v107, v19, v19
	v_mul_f32_e32 v108, v21, v21
	v_add_f32_e32 v103, v103, v104
	v_add_f32_e32 v106, v109, v110
	v_fmac_f32_e32 v107, v18, v18
	v_fmac_f32_e32 v108, v20, v20
	v_add_f32_e32 v103, v103, v105
	v_add_f32_e32 v104, v107, v108
	v_add_f32_e32 v103, v103, v106
	v_add_f32_e32 v103, v103, v104
	s_waitcnt vmcnt(10)
	v_mul_f32_e32 v109, v15, v15
	v_mul_f32_e32 v110, v17, v17
	s_waitcnt vmcnt(9)
	v_mul_f32_e32 v111, v11, v11
	v_mul_f32_e32 v112, v13, v13
	v_fmac_f32_e32 v109, v14, v14
	v_fmac_f32_e32 v110, v16, v16
	s_waitcnt vmcnt(8)
	v_mul_f32_e32 v113, v7, v7
	v_mul_f32_e32 v114, v9, v9
	v_fmac_f32_e32 v111, v10, v10
	v_fmac_f32_e32 v112, v12, v12
	v_add_f32_e32 v105, v109, v110
	s_waitcnt vmcnt(7)
	v_mul_f32_e32 v115, v63, v63
	v_mul_f32_e32 v116, v65, v65
	v_fmac_f32_e32 v113, v6, v6
	v_fmac_f32_e32 v114, v8, v8
	v_add_f32_e32 v107, v111, v112
	v_add_f32_e32 v103, v103, v105
	s_waitcnt vmcnt(6)
	v_mul_f32_e32 v117, v55, v55
	v_mul_f32_e32 v118, v57, v57
	v_fmac_f32_e32 v115, v62, v62
	v_fmac_f32_e32 v116, v64, v64
	v_add_f32_e32 v108, v113, v114
	v_add_f32_e32 v103, v103, v107
	s_waitcnt vmcnt(5)
	v_mul_f32_e32 v119, v51, v51
	v_mul_f32_e32 v120, v53, v53
	v_fmac_f32_e32 v117, v54, v54
	v_fmac_f32_e32 v118, v56, v56
	v_add_f32_e32 v109, v115, v116
	v_add_f32_e32 v103, v103, v108
	v_fmac_f32_e32 v119, v50, v50
	v_fmac_f32_e32 v120, v52, v52
	v_add_f32_e32 v110, v117, v118
	v_add_f32_e32 v103, v103, v109
	s_waitcnt vmcnt(4)
	v_mul_f32_e32 v104, v43, v43
	v_mul_f32_e32 v105, v45, v45
	v_add_f32_e32 v111, v119, v120
	v_add_f32_e32 v103, v103, v110
	v_fmac_f32_e32 v104, v42, v42
	v_fmac_f32_e32 v105, v44, v44
	v_add_f32_e32 v103, v103, v111
	v_add_f32_e32 v104, v104, v105
	v_add_f32_e32 v103, v103, v104
	s_waitcnt vmcnt(3)
	v_mul_f32_e32 v104, v31, v31
	v_mul_f32_e32 v105, v33, v33
	v_fmac_f32_e32 v104, v30, v30
	v_fmac_f32_e32 v105, v32, v32
	v_add_f32_e32 v104, v104, v105
	v_add_f32_e32 v103, v103, v104
	s_waitcnt vmcnt(2)
	v_mul_f32_e32 v104, v35, v35
	v_mul_f32_e32 v105, v37, v37
	v_fmac_f32_e32 v104, v34, v34
	v_fmac_f32_e32 v105, v36, v36
	v_add_f32_e32 v104, v104, v105
	v_add_f32_e32 v103, v103, v104
	s_waitcnt vmcnt(0)
	v_mul_f32_e32 v104, v23, v23
	v_mul_f32_e32 v105, v25, v25
	v_fmac_f32_e32 v104, v22, v22
	v_fmac_f32_e32 v105, v24, v24
	v_add_f32_e32 v104, v104, v105
	v_add_f32_e32 v103, v103, v104
	global_load_dwordx4 v[104:107], v[70:71], off
	v_mul_f32_e32 v108, v3, v3
	v_mul_f32_e32 v109, v5, v5
	v_fmac_f32_e32 v108, v2, v2
	v_fmac_f32_e32 v109, v4, v4
	v_add_f32_e32 v108, v108, v109
	v_add_f32_e32 v103, v103, v108
	ds_bpermute_b32 v108, v1, v103
	s_waitcnt lgkmcnt(0)
	v_add_f32_e32 v103, v103, v108
	ds_bpermute_b32 v108, v96, v103
	s_waitcnt lgkmcnt(0)
	v_add_f32_e32 v103, v103, v108
	ds_bpermute_b32 v108, v97, v103
	s_waitcnt lgkmcnt(0)
	v_add_f32_e32 v103, v103, v108
	ds_bpermute_b32 v108, v98, v103
	s_waitcnt lgkmcnt(0)
	v_add_f32_e32 v103, v103, v108
	ds_bpermute_b32 v108, v99, v103
	s_waitcnt lgkmcnt(0)
	v_add_f32_e32 v103, v103, v108
	ds_bpermute_b32 v108, v100, v103
	s_waitcnt lgkmcnt(0)
	v_add_f32_e32 v103, v103, v108
	v_fmamk_f32 v103, v103, 0x39800000, v101
	v_mul_f32_e32 v108, 0x4f800000, v103
	v_cmp_gt_f32_e32 vcc, s29, v103
	s_nop 1
	v_cndmask_b32_e32 v103, v103, v108, vcc
	v_sqrt_f32_e32 v108, v103
	s_nop 0
	v_add_u32_e32 v109, -1, v108
	v_fma_f32 v110, -v109, v108, v103
	v_cmp_ge_f32_e64 s[0:1], 0, v110
	v_add_u32_e32 v110, 1, v108
	s_nop 0
	v_cndmask_b32_e64 v109, v108, v109, s[0:1]
	v_fma_f32 v108, -v110, v108, v103
	v_cmp_lt_f32_e64 s[0:1], 0, v108
	s_nop 1
	v_cndmask_b32_e64 v108, v109, v110, s[0:1]
	v_mul_f32_e32 v109, 0x37800000, v108
	v_cndmask_b32_e32 v108, v108, v109, vcc
	v_cmp_class_f32_e32 vcc, v103, v102
	s_nop 1
	v_cndmask_b32_e32 v103, v108, v103, vcc
	v_div_scale_f32 v108, s[0:1], v103, v103, 1.0
	v_rcp_f32_e32 v109, v108
	s_lshl_b64 s[0:1], s[18:19], 13
	s_add_u32 s16, s16, s10
	s_addc_u32 s17, s17, s11
	v_fma_f32 v110, -v108, v109, 1.0
	v_fmac_f32_e32 v109, v110, v109
	v_div_scale_f32 v110, vcc, 1.0, v103, 1.0
	v_mul_f32_e32 v111, v110, v109
	v_fma_f32 v112, -v108, v111, v110
	v_fmac_f32_e32 v111, v112, v109
	v_fma_f32 v108, -v108, v111, v110
	v_div_fmas_f32 v108, v108, v109, v111
	v_div_fixup_f32 v103, v108, v103, 1.0
	v_mul_f32_e32 v58, v103, v58
	v_mul_f32_e32 v59, v103, v59
	v_mul_f32_e32 v60, v103, v60
	v_mul_f32_e32 v61, v103, v61
	s_waitcnt vmcnt(0)
	v_mul_f32_e32 v58, v104, v58
	v_mul_f32_e32 v59, v105, v59
	v_lshl_add_u64 v[104:105], v[68:69], 0, s[0:1]
	v_mul_f32_e32 v60, v106, v60
	v_mul_f32_e32 v61, v107, v61
	v_cvt_pk_bf16_f32 v58, v58, v59
	v_cvt_pk_bf16_f32 v59, v60, v61
	global_store_dwordx2 v[104:105], v[58:59], off
	global_load_dwordx4 v[58:61], v[70:71], off offset:1024
	v_mul_f32_e32 v46, v103, v46
	v_mul_f32_e32 v47, v103, v47
	v_mul_f32_e32 v48, v103, v48
	v_mul_f32_e32 v49, v103, v49
	v_mul_f32_e32 v38, v103, v38
	v_mul_f32_e32 v39, v103, v39
	v_mul_f32_e32 v40, v103, v40
	v_mul_f32_e32 v41, v103, v41
	v_mul_f32_e32 v26, v103, v26
	v_mul_f32_e32 v27, v103, v27
	v_mul_f32_e32 v28, v103, v28
	v_mul_f32_e32 v29, v103, v29
	v_mul_f32_e32 v18, v103, v18
	v_mul_f32_e32 v19, v103, v19
	v_mul_f32_e32 v20, v103, v20
	v_mul_f32_e32 v21, v103, v21
	v_mul_f32_e32 v14, v103, v14
	v_mul_f32_e32 v15, v103, v15
	v_mul_f32_e32 v16, v103, v16
	v_mul_f32_e32 v17, v103, v17
	v_mul_f32_e32 v10, v103, v10
	v_mul_f32_e32 v11, v103, v11
	v_mul_f32_e32 v12, v103, v12
	v_mul_f32_e32 v13, v103, v13
	v_mul_f32_e32 v6, v103, v6
	v_mul_f32_e32 v7, v103, v7
	v_mul_f32_e32 v8, v103, v8
	v_mul_f32_e32 v9, v103, v9
	s_add_u32 s12, s12, s14
	s_addc_u32 s13, s13, s15
	v_mul_f32_e32 v2, v103, v2
	v_mul_f32_e32 v3, v103, v3
	v_mul_f32_e32 v4, v103, v4
	v_mul_f32_e32 v5, v103, v5
	s_cmpk_gt_i32 s16, 0x47ff
	s_waitcnt vmcnt(0)
	v_mul_f32_e32 v46, v58, v46
	v_mul_f32_e32 v47, v59, v47
	v_mul_f32_e32 v48, v60, v48
	v_mul_f32_e32 v49, v61, v49
	v_cvt_pk_bf16_f32 v46, v46, v47
	v_cvt_pk_bf16_f32 v47, v48, v49
	global_store_dwordx2 v[104:105], v[46:47], off offset:512
	global_load_dwordx4 v[46:49], v[70:71], off offset:2048
	s_waitcnt vmcnt(0)
	v_mul_f32_e32 v38, v46, v38
	v_mul_f32_e32 v39, v47, v39
	v_mul_f32_e32 v40, v48, v40
	v_mul_f32_e32 v41, v49, v41
	v_cvt_pk_bf16_f32 v38, v38, v39
	v_cvt_pk_bf16_f32 v39, v40, v41
	global_store_dwordx2 v[104:105], v[38:39], off offset:1024
	global_load_dwordx4 v[38:41], v[70:71], off offset:3072
	s_waitcnt vmcnt(0)
	v_mul_f32_e32 v26, v38, v26
	v_mul_f32_e32 v27, v39, v27
	v_mul_f32_e32 v28, v40, v28
	v_mul_f32_e32 v29, v41, v29
	v_cvt_pk_bf16_f32 v26, v26, v27
	v_cvt_pk_bf16_f32 v27, v28, v29
	global_store_dwordx2 v[104:105], v[26:27], off offset:1536
	global_load_dwordx4 v[26:29], v[72:73], off
	s_waitcnt vmcnt(0)
	v_mul_f32_e32 v18, v26, v18
	v_mul_f32_e32 v19, v27, v19
	v_mul_f32_e32 v20, v28, v20
	v_mul_f32_e32 v21, v29, v21
	v_cvt_pk_bf16_f32 v18, v18, v19
	v_cvt_pk_bf16_f32 v19, v20, v21
	global_store_dwordx2 v[104:105], v[18:19], off offset:2048
	global_load_dwordx4 v[18:21], v[74:75], off
	s_waitcnt vmcnt(0)
	v_mul_f32_e32 v14, v18, v14
	v_mul_f32_e32 v15, v19, v15
	v_mul_f32_e32 v16, v20, v16
	v_mul_f32_e32 v17, v21, v17
	v_cvt_pk_bf16_f32 v14, v14, v15
	v_cvt_pk_bf16_f32 v15, v16, v17
	global_store_dwordx2 v[104:105], v[14:15], off offset:2560
	global_load_dwordx4 v[14:17], v[76:77], off
	s_waitcnt vmcnt(0)
	v_mul_f32_e32 v10, v14, v10
	v_mul_f32_e32 v11, v15, v11
	v_mul_f32_e32 v12, v16, v12
	v_mul_f32_e32 v13, v17, v13
	v_cvt_pk_bf16_f32 v10, v10, v11
	v_cvt_pk_bf16_f32 v11, v12, v13
	global_store_dwordx2 v[104:105], v[10:11], off offset:3072
	global_load_dwordx4 v[10:13], v[78:79], off
	v_mul_f32_e32 v14, v103, v64
	v_mul_f32_e32 v15, v103, v65
	s_waitcnt vmcnt(0)
	v_mul_f32_e32 v6, v10, v6
	v_mul_f32_e32 v7, v11, v7
	v_mul_f32_e32 v8, v12, v8
	v_mul_f32_e32 v9, v13, v9
	v_cvt_pk_bf16_f32 v6, v6, v7
	v_cvt_pk_bf16_f32 v7, v8, v9
	global_store_dwordx2 v[104:105], v[6:7], off offset:3584
	global_load_dwordx4 v[6:9], v[80:81], off
	v_add_co_u32_e32 v10, vcc, s20, v104
	v_mul_f32_e32 v12, v103, v62
	v_mul_f32_e32 v13, v103, v63
	v_addc_co_u32_e32 v11, vcc, 0, v105, vcc
	s_waitcnt vmcnt(0)
	v_mul_f32_e32 v6, v6, v12
	v_mul_f32_e32 v7, v7, v13
	v_mul_f32_e32 v8, v8, v14
	v_mul_f32_e32 v9, v9, v15
	v_cvt_pk_bf16_f32 v6, v6, v7
	v_cvt_pk_bf16_f32 v7, v8, v9
	global_store_dwordx2 v[10:11], v[6:7], off
	global_load_dwordx4 v[6:9], v[82:83], off
	v_mul_f32_e32 v12, v103, v54
	v_mul_f32_e32 v13, v103, v55
	v_mul_f32_e32 v14, v103, v56
	v_mul_f32_e32 v15, v103, v57
	s_waitcnt vmcnt(0)
	v_mul_f32_e32 v6, v6, v12
	v_mul_f32_e32 v7, v7, v13
	v_mul_f32_e32 v8, v8, v14
	v_mul_f32_e32 v9, v9, v15
	v_cvt_pk_bf16_f32 v6, v6, v7
	v_cvt_pk_bf16_f32 v7, v8, v9
	global_store_dwordx2 v[10:11], v[6:7], off offset:512
	global_load_dwordx4 v[6:9], v[84:85], off
	v_mul_f32_e32 v12, v103, v50
	v_mul_f32_e32 v13, v103, v51
	v_mul_f32_e32 v14, v103, v52
	v_mul_f32_e32 v15, v103, v53
	s_waitcnt vmcnt(0)
	v_mul_f32_e32 v6, v6, v12
	v_mul_f32_e32 v7, v7, v13
	v_mul_f32_e32 v8, v8, v14
	v_mul_f32_e32 v9, v9, v15
	v_cvt_pk_bf16_f32 v6, v6, v7
	v_cvt_pk_bf16_f32 v7, v8, v9
	global_store_dwordx2 v[10:11], v[6:7], off offset:1024
	global_load_dwordx4 v[6:9], v[86:87], off
	v_mul_f32_e32 v12, v103, v42
	v_mul_f32_e32 v13, v103, v43
	v_mul_f32_e32 v14, v103, v44
	v_mul_f32_e32 v15, v103, v45
	s_waitcnt vmcnt(0)
	v_mul_f32_e32 v6, v6, v12
	v_mul_f32_e32 v7, v7, v13
	v_mul_f32_e32 v8, v8, v14
	v_mul_f32_e32 v9, v9, v15
	v_cvt_pk_bf16_f32 v6, v6, v7
	v_cvt_pk_bf16_f32 v7, v8, v9
	global_store_dwordx2 v[10:11], v[6:7], off offset:1536
	global_load_dwordx4 v[6:9], v[88:89], off
	v_mul_f32_e32 v12, v103, v30
	v_mul_f32_e32 v13, v103, v31
	v_mul_f32_e32 v14, v103, v32
	v_mul_f32_e32 v15, v103, v33
	s_waitcnt vmcnt(0)
	v_mul_f32_e32 v6, v6, v12
	v_mul_f32_e32 v7, v7, v13
	v_mul_f32_e32 v8, v8, v14
	v_mul_f32_e32 v9, v9, v15
	v_cvt_pk_bf16_f32 v6, v6, v7
	v_cvt_pk_bf16_f32 v7, v8, v9
	global_store_dwordx2 v[10:11], v[6:7], off offset:2048
	global_load_dwordx4 v[6:9], v[90:91], off
	v_mul_f32_e32 v12, v103, v34
	v_mul_f32_e32 v13, v103, v35
	v_mul_f32_e32 v14, v103, v36
	v_mul_f32_e32 v15, v103, v37
	s_waitcnt vmcnt(0)
	v_mul_f32_e32 v6, v6, v12
	v_mul_f32_e32 v7, v7, v13
	v_mul_f32_e32 v8, v8, v14
	v_mul_f32_e32 v9, v9, v15
	v_cvt_pk_bf16_f32 v6, v6, v7
	v_cvt_pk_bf16_f32 v7, v8, v9
	global_store_dwordx2 v[10:11], v[6:7], off offset:2560
	global_load_dwordx4 v[6:9], v[92:93], off
	v_mul_f32_e32 v12, v103, v22
	v_mul_f32_e32 v13, v103, v23
	v_mul_f32_e32 v14, v103, v24
	v_mul_f32_e32 v15, v103, v25
	s_waitcnt vmcnt(0)
	v_mul_f32_e32 v6, v6, v12
	v_mul_f32_e32 v7, v7, v13
	v_mul_f32_e32 v8, v8, v14
	v_mul_f32_e32 v9, v9, v15
	v_cvt_pk_bf16_f32 v6, v6, v7
	v_cvt_pk_bf16_f32 v7, v8, v9
	global_store_dwordx2 v[10:11], v[6:7], off offset:3072
	global_load_dwordx4 v[6:9], v[94:95], off
	s_waitcnt vmcnt(0)
	v_mul_f32_e32 v2, v6, v2
	v_mul_f32_e32 v3, v7, v3
	v_mul_f32_e32 v4, v8, v4
	v_mul_f32_e32 v5, v9, v5
	v_cvt_pk_bf16_f32 v2, v2, v3
	v_cvt_pk_bf16_f32 v3, v4, v5
	global_store_dwordx2 v[10:11], v[2:3], off offset:3584
	s_cbranch_scc1 .LBB0_50

.LBB0_52:
	global_load_dwordx4 v[6:9], v[4:5], off offset:-2064 nt
	global_load_dwordx4 v[10:13], v[4:5], off offset:-2048 nt
	s_ashr_i32 s5, s4, 11
	s_and_b32 s9, s4, 0x7ff
	s_mul_hi_i32 s11, s5, 0x840
	s_mulk_i32 s5, 0x840
	s_add_u32 s12, s5, s9
	s_addc_u32 s13, s11, 0
	s_lshl_b64 s[12:13], s[12:13], 11
	v_lshl_add_u64 v[14:15], v[2:3], 0, s[12:13]
	s_add_i32 s4, s4, s10
	s_cmp_gt_i32 s4, 0xffff
	s_waitcnt vmcnt(1)
	v_cvt_pk_bf16_f32 v6, v6, v7
	v_cvt_pk_bf16_f32 v7, v8, v9
	s_waitcnt vmcnt(0)
	v_cvt_pk_bf16_f32 v8, v10, v11
	v_cvt_pk_bf16_f32 v9, v12, v13
	global_store_dwordx4 v[14:15], v[6:9], off
	global_load_dwordx4 v[6:9], v[4:5], off offset:-16 nt
	s_nop 0
	global_load_dwordx4 v[10:13], v[4:5], off nt
	v_lshl_add_u64 v[4:5], v[4:5], 0, s[0:1]
	s_waitcnt vmcnt(1)
	v_cvt_pk_bf16_f32 v6, v6, v7
	v_cvt_pk_bf16_f32 v7, v8, v9
	s_waitcnt vmcnt(0)
	v_cvt_pk_bf16_f32 v8, v10, v11
	v_cvt_pk_bf16_f32 v9, v12, v13
	global_store_dwordx4 v[14:15], v[6:9], off offset:1024
	s_cbranch_scc0 .LBB0_52
